# tile headers: group-height division replaced by shift/mask (height is always 8); relaxed first-iteration waits for w_in/residual loops placed in the peeled iteration only
# baseline (speedup 1.0000x reference)
.LBB0_563:
	s_add_i32 s45, s2, 1
	s_mul_i32 s3, s45, s70
	s_mul_hi_u32 s10, s45, s56
	s_add_i32 s10, s10, s3
	s_mul_i32 s3, s45, s56
	s_add_u32 s26, s3, s74
	s_addc_u32 s27, s10, s75
	v_mov_b64_e32 v[2:3], 0x480
	v_cmp_lt_i64_e64 s[10:11], s[26:27], v[2:3]
	v_mov_b64_e32 v[2:3], 0x47f
	v_cmp_gt_i64_e32 vcc, s[26:27], v[2:3]
	s_cbranch_vccnz .LBB0_565
	s_ashr_i32 s3, s26, 31
	s_lshr_b32 s3, s3, 29
	s_add_i32 s3, s26, s3
	s_ashr_i32 s22, s3, 3
	s_and_b32 s3, s3, -8
	s_sub_i32 s3, s26, s3
	s_cmp_lt_i32 s3, 0
	s_movk_i32 s23, 0x91
	s_cselect_b32 s23, s23, 0x90
	s_mul_i32 s3, s3, s23
	s_add_i32 s3, s3, s22
	s_mul_hi_i32 s22, s3, 0x38e38e39
	s_lshr_b32 s23, s22, 31
	s_ashr_i32 s22, s22, 4
	s_add_i32 s22, s22, s23
	s_lshl_b32 s23, s22, 3
	s_mulk_i32 s22, 0x48
	s_sub_i32 s3, s3, s22
	s_lshr_b32 s22, s3, 3
	s_and_b32 s3, s3, 7
	s_add_i32 s24, s23, s3
.LBB0_565:
	s_ashr_i32 s25, s24, 31
	s_lshl_b64 s[26:27], s[24:25], 19
	s_add_u32 s26, s84, s26
	s_addc_u32 s27, s85, s27
	s_and_b64 s[28:29], s[10:11], exec
	s_cselect_b32 s3, s27, s1
	s_cselect_b32 s25, s26, s0
	s_ashr_i32 s23, s22, 31
	s_lshl_b64 s[28:29], s[22:23], 19
	s_add_u32 s28, s37, s28
	s_addc_u32 s29, s38, s29
	s_and_b64 s[34:35], s[10:11], exec
	s_cselect_b32 s23, s29, s31
	s_cselect_b32 s48, s28, s30
	s_add_u32 s0, s0, 0x40080
	s_addc_u32 s1, s1, 0
	s_add_u32 s49, s30, 0x100
	s_addc_u32 s50, s31, 0
	s_mov_b32 s51, -2
	s_waitcnt lgkmcnt(0)
	s_add_u32 s30, s0, 0xfffc0080
	s_addc_u32 s31, s1, -1
	s_add_i32 s52, 0, 0x10000
	s_cmp_eq_u32 s51, 12
	s_cselect_b32 s35, s3, s31
	s_cselect_b32 s34, s25, s30
	s_cselect_b32 s31, s23, s50
	s_cselect_b32 s30, s48, s49
	s_add_i32 s54, 0, 0x14000
	v_add_u32_e32 v158, s52, v199
	v_add_u32_e32 v174, s54, v199
	ds_read_b128 v[134:137], v158
	ds_read_b128 v[150:153], v158 offset:1024
	ds_read_b128 v[154:157], v158 offset:2048
	ds_read_b128 v[158:161], v158 offset:3072
	ds_read_b128 v[162:165], v174
	ds_read_b128 v[166:169], v174 offset:1024
	ds_read_b128 v[170:173], v174 offset:2048
	ds_read_b128 v[182:185], v174 offset:3072
	v_lshl_add_u64 v[174:175], s[0:1], 0, v[146:147]
	s_add_i32 m0, s39, 0xc000
	ds_read_b128 v[186:189], v201
	ds_read_b128 v[202:205], v201 offset:1024
	ds_read_b128 v[206:209], v201 offset:2048
	ds_read_b128 v[210:213], v201 offset:3072
	ds_read_b128 v[214:217], v201 offset:4096
	ds_read_b128 v[218:221], v201 offset:5120
	ds_read_b128 v[222:225], v201 offset:6144
	ds_read_b128 v[226:229], v201 offset:7168
	global_load_lds_dwordx4 v[174:175], off
	v_lshl_add_u64 v[174:175], s[0:1], 0, v[148:149]
	s_add_i32 m0, s39, 0xe000
	s_nop 0
	global_load_lds_dwordx4 v[174:175], off
	s_cmp_lg_u32 s2, 0
	s_cbranch_scc1 .Lpl1_relax_1
	s_waitcnt vmcnt(8)
	s_branch .Lpl1_join_1

.Lpl1_join_1:
	s_waitcnt lgkmcnt(0)
	s_barrier
	s_setprio 1
	s_waitcnt lgkmcnt(0)
	v_mfma_f32_16x16x32_bf16 v[130:133], v[134:137], v[186:189], 0
	v_mfma_f32_16x16x32_bf16 v[130:133], v[150:153], v[202:205], v[130:133]
	v_mfma_f32_16x16x32_bf16 v[126:129], v[154:157], v[186:189], 0
	v_mfma_f32_16x16x32_bf16 v[126:129], v[158:161], v[202:205], v[126:129]
	v_mfma_f32_16x16x32_bf16 v[114:117], v[134:137], v[206:209], 0
	v_mfma_f32_16x16x32_bf16 v[114:117], v[150:153], v[210:213], v[114:117]
	v_mfma_f32_16x16x32_bf16 v[110:113], v[154:157], v[206:209], 0
	v_mfma_f32_16x16x32_bf16 v[110:113], v[158:161], v[210:213], v[110:113]
	v_mfma_f32_16x16x32_bf16 v[98:101], v[134:137], v[214:217], 0
	v_mfma_f32_16x16x32_bf16 v[98:101], v[150:153], v[218:221], v[98:101]
	v_mfma_f32_16x16x32_bf16 v[94:97], v[154:157], v[214:217], 0
	v_mfma_f32_16x16x32_bf16 v[94:97], v[158:161], v[218:221], v[94:97]
	v_mfma_f32_16x16x32_bf16 v[82:85], v[134:137], v[222:225], 0
	v_mfma_f32_16x16x32_bf16 v[82:85], v[150:153], v[226:229], v[82:85]
	v_mfma_f32_16x16x32_bf16 v[78:81], v[154:157], v[222:225], 0
	v_mfma_f32_16x16x32_bf16 v[78:81], v[158:161], v[226:229], v[78:81]
	s_setprio 0
	s_setprio 1
	v_mfma_f32_16x16x32_bf16 v[122:125], v[162:165], v[186:189], 0
	v_mfma_f32_16x16x32_bf16 v[122:125], v[166:169], v[202:205], v[122:125]
	v_mfma_f32_16x16x32_bf16 v[118:121], v[170:173], v[186:189], 0
	v_mfma_f32_16x16x32_bf16 v[118:121], v[182:185], v[202:205], v[118:121]
	v_mfma_f32_16x16x32_bf16 v[106:109], v[162:165], v[206:209], 0
	v_mfma_f32_16x16x32_bf16 v[106:109], v[166:169], v[210:213], v[106:109]
	v_mfma_f32_16x16x32_bf16 v[102:105], v[170:173], v[206:209], 0
	v_mfma_f32_16x16x32_bf16 v[102:105], v[182:185], v[210:213], v[102:105]
	v_mfma_f32_16x16x32_bf16 v[90:93], v[162:165], v[214:217], 0
	v_mfma_f32_16x16x32_bf16 v[90:93], v[166:169], v[218:221], v[90:93]
	v_mfma_f32_16x16x32_bf16 v[86:89], v[170:173], v[214:217], 0
	v_mfma_f32_16x16x32_bf16 v[86:89], v[182:185], v[218:221], v[86:89]
	v_mfma_f32_16x16x32_bf16 v[74:77], v[162:165], v[222:225], 0
	v_mfma_f32_16x16x32_bf16 v[74:77], v[166:169], v[226:229], v[74:77]
	v_mfma_f32_16x16x32_bf16 v[70:73], v[170:173], v[222:225], 0
	v_mfma_f32_16x16x32_bf16 v[70:73], v[182:185], v[226:229], v[70:73]
	s_setprio 0
	s_barrier
	s_add_i32 s52, s52, s36
	v_lshl_add_u64 v[174:175], s[30:31], 0, v[0:1]
	s_mov_b32 m0, s52
	ds_read_b128 v[186:189], v201 offset:16384
	ds_read_b128 v[202:205], v201 offset:17408
	ds_read_b128 v[206:209], v201 offset:18432
	ds_read_b128 v[210:213], v201 offset:19456
	ds_read_b128 v[214:217], v201 offset:20480
	ds_read_b128 v[218:221], v201 offset:21504
	ds_read_b128 v[222:225], v201 offset:22528
	ds_read_b128 v[226:229], v201 offset:23552
	global_load_lds_dwordx4 v[174:175], off
	s_add_i32 m0, s52, 0x2000
	s_add_u32 s52, s30, 0x40000
	v_lshl_add_u64 v[190:191], s[30:31], 0, v[14:15]
	s_addc_u32 s53, s31, 0
	s_add_i32 s54, s54, s36
	global_load_lds_dwordx4 v[190:191], off
	v_lshl_add_u64 v[230:231], s[52:53], 0, v[0:1]
	s_mov_b32 m0, s54
	v_lshl_add_u64 v[232:233], s[34:35], 0, v[138:139]
	global_load_lds_dwordx4 v[230:231], off
	v_lshl_add_u64 v[230:231], s[52:53], 0, v[14:15]
	s_add_i32 m0, s54, 0x2000
	s_nop 0
	global_load_lds_dwordx4 v[230:231], off
	v_lshl_add_u64 v[230:231], s[34:35], 0, v[140:141]
	s_mov_b32 m0, s39
	s_nop 0
	global_load_lds_dwordx4 v[230:231], off
	s_mov_b32 m0, s40
	s_nop 0
	global_load_lds_dwordx4 v[232:233], off
	s_cmp_lg_u32 s2, 0
	s_cbranch_scc1 .Lpl1_relax_2
	s_waitcnt vmcnt(8)
	s_branch .Lpl1_join_2

.Lpl1_join_2:
	s_waitcnt lgkmcnt(0)
	s_barrier
	s_setprio 1
	s_waitcnt lgkmcnt(0)
	v_mfma_f32_16x16x32_bf16 v[66:69], v[134:137], v[186:189], 0
	v_mfma_f32_16x16x32_bf16 v[66:69], v[150:153], v[202:205], v[66:69]
	v_mfma_f32_16x16x32_bf16 v[62:65], v[154:157], v[186:189], 0
	v_mfma_f32_16x16x32_bf16 v[62:65], v[158:161], v[202:205], v[62:65]
	v_mfma_f32_16x16x32_bf16 v[50:53], v[134:137], v[206:209], 0
	v_mfma_f32_16x16x32_bf16 v[50:53], v[150:153], v[210:213], v[50:53]
	v_mfma_f32_16x16x32_bf16 v[46:49], v[154:157], v[206:209], 0
	v_mfma_f32_16x16x32_bf16 v[46:49], v[158:161], v[210:213], v[46:49]
	v_mfma_f32_16x16x32_bf16 v[34:37], v[134:137], v[214:217], 0
	v_mfma_f32_16x16x32_bf16 v[34:37], v[150:153], v[218:221], v[34:37]
	v_mfma_f32_16x16x32_bf16 v[30:33], v[154:157], v[214:217], 0
	v_mfma_f32_16x16x32_bf16 v[30:33], v[158:161], v[218:221], v[30:33]
	v_mfma_f32_16x16x32_bf16 v[18:21], v[134:137], v[222:225], 0
	v_mfma_f32_16x16x32_bf16 v[18:21], v[150:153], v[226:229], v[18:21]
	v_mfma_f32_16x16x32_bf16 v[10:13], v[154:157], v[222:225], 0
	v_mfma_f32_16x16x32_bf16 v[10:13], v[158:161], v[226:229], v[10:13]
	s_setprio 0
	s_setprio 1
	v_mfma_f32_16x16x32_bf16 v[58:61], v[162:165], v[186:189], 0
	v_mfma_f32_16x16x32_bf16 v[58:61], v[166:169], v[202:205], v[58:61]
	v_mfma_f32_16x16x32_bf16 v[54:57], v[170:173], v[186:189], 0
	v_mfma_f32_16x16x32_bf16 v[54:57], v[182:185], v[202:205], v[54:57]
	v_mfma_f32_16x16x32_bf16 v[42:45], v[162:165], v[206:209], 0
	v_mfma_f32_16x16x32_bf16 v[42:45], v[166:169], v[210:213], v[42:45]
	v_mfma_f32_16x16x32_bf16 v[38:41], v[170:173], v[206:209], 0
	v_mfma_f32_16x16x32_bf16 v[38:41], v[182:185], v[210:213], v[38:41]
	v_mfma_f32_16x16x32_bf16 v[26:29], v[162:165], v[214:217], 0
	v_mfma_f32_16x16x32_bf16 v[26:29], v[166:169], v[218:221], v[26:29]
	v_mfma_f32_16x16x32_bf16 v[22:25], v[170:173], v[214:217], 0
	v_mfma_f32_16x16x32_bf16 v[22:25], v[182:185], v[218:221], v[22:25]
	v_mfma_f32_16x16x32_bf16 v[6:9], v[162:165], v[222:225], 0
	v_mfma_f32_16x16x32_bf16 v[6:9], v[166:169], v[226:229], v[6:9]
	v_mfma_f32_16x16x32_bf16 v[2:5], v[170:173], v[222:225], 0
	v_mfma_f32_16x16x32_bf16 v[2:5], v[182:185], v[226:229], v[2:5]
	s_setprio 0
	s_barrier
	s_add_i32 s52, 0, 0x18000
	s_add_i32 s53, 0, 0x1c000
	v_add_u32_e32 v158, s52, v199
	v_add_u32_e32 v182, s53, v199
	ds_read_b128 v[134:137], v158
	ds_read_b128 v[150:153], v158 offset:1024
	ds_read_b128 v[154:157], v158 offset:2048
	ds_read_b128 v[158:161], v158 offset:3072
	ds_read_b128 v[162:165], v182
	ds_read_b128 v[166:169], v182 offset:1024
	ds_read_b128 v[170:173], v182 offset:2048
	ds_read_b128 v[182:185], v182 offset:3072
	s_add_u32 s34, s34, 0x40000
	s_addc_u32 s35, s35, 0
	s_mov_b32 m0, s41
	v_lshl_add_u64 v[234:235], s[34:35], 0, v[140:141]
	ds_read_b128 v[186:189], v201 offset:32768
	ds_read_b128 v[202:205], v201 offset:33792
	ds_read_b128 v[206:209], v201 offset:34816
	ds_read_b128 v[210:213], v201 offset:35840
	ds_read_b128 v[214:217], v201 offset:36864
	ds_read_b128 v[218:221], v201 offset:37888
	ds_read_b128 v[222:225], v201 offset:38912
	ds_read_b128 v[226:229], v201 offset:39936
	global_load_lds_dwordx4 v[234:235], off
	v_lshl_add_u64 v[234:235], s[34:35], 0, v[138:139]
	s_mov_b32 m0, s42
	s_nop 0
	global_load_lds_dwordx4 v[234:235], off
	s_waitcnt vmcnt(8)
	s_waitcnt lgkmcnt(0)
	s_barrier
	s_setprio 1
	s_waitcnt lgkmcnt(0)
	v_mfma_f32_16x16x32_bf16 v[130:133], v[134:137], v[186:189], v[130:133]
	v_mfma_f32_16x16x32_bf16 v[130:133], v[150:153], v[202:205], v[130:133]
	v_mfma_f32_16x16x32_bf16 v[126:129], v[154:157], v[186:189], v[126:129]
	v_mfma_f32_16x16x32_bf16 v[126:129], v[158:161], v[202:205], v[126:129]
	v_mfma_f32_16x16x32_bf16 v[114:117], v[134:137], v[206:209], v[114:117]
	v_mfma_f32_16x16x32_bf16 v[114:117], v[150:153], v[210:213], v[114:117]
	v_mfma_f32_16x16x32_bf16 v[110:113], v[154:157], v[206:209], v[110:113]
	v_mfma_f32_16x16x32_bf16 v[110:113], v[158:161], v[210:213], v[110:113]
	v_mfma_f32_16x16x32_bf16 v[98:101], v[134:137], v[214:217], v[98:101]
	v_mfma_f32_16x16x32_bf16 v[98:101], v[150:153], v[218:221], v[98:101]
	v_mfma_f32_16x16x32_bf16 v[94:97], v[154:157], v[214:217], v[94:97]
	v_mfma_f32_16x16x32_bf16 v[94:97], v[158:161], v[218:221], v[94:97]
	v_mfma_f32_16x16x32_bf16 v[82:85], v[134:137], v[222:225], v[82:85]
	v_mfma_f32_16x16x32_bf16 v[82:85], v[150:153], v[226:229], v[82:85]
	v_mfma_f32_16x16x32_bf16 v[78:81], v[154:157], v[222:225], v[78:81]
	v_mfma_f32_16x16x32_bf16 v[78:81], v[158:161], v[226:229], v[78:81]
	s_setprio 0
	s_setprio 1
	v_mfma_f32_16x16x32_bf16 v[122:125], v[162:165], v[186:189], v[122:125]
	v_mfma_f32_16x16x32_bf16 v[122:125], v[166:169], v[202:205], v[122:125]
	v_mfma_f32_16x16x32_bf16 v[118:121], v[170:173], v[186:189], v[118:121]
	v_mfma_f32_16x16x32_bf16 v[118:121], v[182:185], v[202:205], v[118:121]
	v_mfma_f32_16x16x32_bf16 v[106:109], v[162:165], v[206:209], v[106:109]
	v_mfma_f32_16x16x32_bf16 v[106:109], v[166:169], v[210:213], v[106:109]
	v_mfma_f32_16x16x32_bf16 v[102:105], v[170:173], v[206:209], v[102:105]
	v_mfma_f32_16x16x32_bf16 v[102:105], v[182:185], v[210:213], v[102:105]
	v_mfma_f32_16x16x32_bf16 v[90:93], v[162:165], v[214:217], v[90:93]
	v_mfma_f32_16x16x32_bf16 v[90:93], v[166:169], v[218:221], v[90:93]
	v_mfma_f32_16x16x32_bf16 v[86:89], v[170:173], v[214:217], v[86:89]
	v_mfma_f32_16x16x32_bf16 v[86:89], v[182:185], v[218:221], v[86:89]
	v_mfma_f32_16x16x32_bf16 v[74:77], v[162:165], v[222:225], v[74:77]
	v_mfma_f32_16x16x32_bf16 v[74:77], v[166:169], v[226:229], v[74:77]
	v_mfma_f32_16x16x32_bf16 v[70:73], v[170:173], v[222:225], v[70:73]
	v_mfma_f32_16x16x32_bf16 v[70:73], v[182:185], v[226:229], v[70:73]
	s_setprio 0
	s_barrier
	s_add_i32 s34, s52, s36
	v_lshl_add_u64 v[174:175], v[174:175], 0, s[92:93]
	s_mov_b32 m0, s34
	ds_read_b128 v[186:189], v201 offset:49152
	ds_read_b128 v[202:205], v201 offset:50176
	ds_read_b128 v[206:209], v201 offset:51200
	ds_read_b128 v[210:213], v201 offset:52224
	ds_read_b128 v[214:217], v201 offset:53248
	ds_read_b128 v[218:221], v201 offset:54272
	ds_read_b128 v[222:225], v201 offset:55296
	ds_read_b128 v[226:229], v201 offset:56320
	global_load_lds_dwordx4 v[174:175], off
	s_add_i32 m0, s34, 0x2000
	s_add_u32 s30, s30, 0x40080
	v_lshl_add_u64 v[174:175], v[190:191], 0, s[92:93]
	s_addc_u32 s31, s31, 0
	s_add_i32 s34, s53, s36
	global_load_lds_dwordx4 v[174:175], off
	v_lshl_add_u64 v[174:175], s[30:31], 0, v[0:1]
	s_mov_b32 m0, s34
	s_nop 0
	global_load_lds_dwordx4 v[174:175], off
	v_lshl_add_u64 v[174:175], s[30:31], 0, v[14:15]
	s_add_i32 m0, s34, 0x2000
	s_nop 0
	global_load_lds_dwordx4 v[174:175], off
	v_lshl_add_u64 v[174:175], v[230:231], 0, s[92:93]
	s_mov_b32 m0, s43
	s_nop 0
	global_load_lds_dwordx4 v[174:175], off
	v_lshl_add_u64 v[174:175], v[232:233], 0, s[92:93]
	s_mov_b32 m0, s44
	s_nop 0
	global_load_lds_dwordx4 v[174:175], off
	s_waitcnt vmcnt(8)
	s_waitcnt lgkmcnt(0)
	s_barrier
	s_setprio 1
	s_waitcnt lgkmcnt(0)
	v_mfma_f32_16x16x32_bf16 v[66:69], v[134:137], v[186:189], v[66:69]
	v_mfma_f32_16x16x32_bf16 v[66:69], v[150:153], v[202:205], v[66:69]
	v_mfma_f32_16x16x32_bf16 v[62:65], v[154:157], v[186:189], v[62:65]
	v_mfma_f32_16x16x32_bf16 v[62:65], v[158:161], v[202:205], v[62:65]
	v_mfma_f32_16x16x32_bf16 v[50:53], v[134:137], v[206:209], v[50:53]
	v_mfma_f32_16x16x32_bf16 v[50:53], v[150:153], v[210:213], v[50:53]
	v_mfma_f32_16x16x32_bf16 v[46:49], v[154:157], v[206:209], v[46:49]
	v_mfma_f32_16x16x32_bf16 v[46:49], v[158:161], v[210:213], v[46:49]
	v_mfma_f32_16x16x32_bf16 v[34:37], v[134:137], v[214:217], v[34:37]
	v_mfma_f32_16x16x32_bf16 v[34:37], v[150:153], v[218:221], v[34:37]
	v_mfma_f32_16x16x32_bf16 v[30:33], v[154:157], v[214:217], v[30:33]
	v_mfma_f32_16x16x32_bf16 v[30:33], v[158:161], v[218:221], v[30:33]
	v_mfma_f32_16x16x32_bf16 v[18:21], v[134:137], v[222:225], v[18:21]
	v_mfma_f32_16x16x32_bf16 v[18:21], v[150:153], v[226:229], v[18:21]
	v_mfma_f32_16x16x32_bf16 v[10:13], v[154:157], v[222:225], v[10:13]
	v_mfma_f32_16x16x32_bf16 v[10:13], v[158:161], v[226:229], v[10:13]
	s_setprio 0
	s_setprio 1
	v_mfma_f32_16x16x32_bf16 v[58:61], v[162:165], v[186:189], v[58:61]
	v_mfma_f32_16x16x32_bf16 v[58:61], v[166:169], v[202:205], v[58:61]
	v_mfma_f32_16x16x32_bf16 v[54:57], v[170:173], v[186:189], v[54:57]
	v_mfma_f32_16x16x32_bf16 v[54:57], v[182:185], v[202:205], v[54:57]
	v_mfma_f32_16x16x32_bf16 v[42:45], v[162:165], v[206:209], v[42:45]
	v_mfma_f32_16x16x32_bf16 v[42:45], v[166:169], v[210:213], v[42:45]
	v_mfma_f32_16x16x32_bf16 v[38:41], v[170:173], v[206:209], v[38:41]
	v_mfma_f32_16x16x32_bf16 v[38:41], v[182:185], v[210:213], v[38:41]
	v_mfma_f32_16x16x32_bf16 v[26:29], v[162:165], v[214:217], v[26:29]
	v_mfma_f32_16x16x32_bf16 v[26:29], v[166:169], v[218:221], v[26:29]
	v_mfma_f32_16x16x32_bf16 v[22:25], v[170:173], v[214:217], v[22:25]
	v_mfma_f32_16x16x32_bf16 v[22:25], v[182:185], v[218:221], v[22:25]
	v_mfma_f32_16x16x32_bf16 v[6:9], v[162:165], v[222:225], v[6:9]
	v_mfma_f32_16x16x32_bf16 v[6:9], v[166:169], v[226:229], v[6:9]
	v_mfma_f32_16x16x32_bf16 v[2:5], v[170:173], v[222:225], v[2:5]
	v_mfma_f32_16x16x32_bf16 v[2:5], v[182:185], v[226:229], v[2:5]
	s_setprio 0
	s_barrier
	s_add_i32 s51, s51, 2
	s_add_u32 s0, s0, 0x100
	s_addc_u32 s1, s1, 0
	s_add_u32 s49, s49, 0x100
	s_addc_u32 s50, s50, 0
	s_cmp_gt_u32 s51, 13
	s_cbranch_scc1 .Lpeel_exit_1

.LBB0_631:
	s_ashr_i32 s4, s11, 3
	s_add_i32 s4, s21, s4
	s_ashr_i32 s5, s4, 31
	s_lshr_b32 s5, s5, 27
	s_add_i32 s5, s4, s5
	s_ashr_i32 s11, s5, 5
	s_lshl_b32 s20, s11, 3
	s_andn2_b32 s5, s5, 31
	s_sub_i32 s4, s4, s5
	s_lshr_b32 s11, s4, 3
	s_and_b32 s4, s4, 7
	s_add_i32 s44, s20, s4

.LBB0_636:
	s_add_u32 s22, s22, 0x80
	s_addc_u32 s23, s23, 0
	s_add_u32 s45, s24, 0x100
	s_addc_u32 s46, s25, 0
	s_mov_b32 s24, 0
	s_add_i32 s47, s24, 2
	s_add_u32 s48, s22, 0x80
	s_addc_u32 s25, s23, 0
	s_add_i32 s50, 0, 0x10000
	s_cmp_eq_u32 s40, s24
	s_cselect_b32 s25, s7, s25
	s_cselect_b32 s24, s6, s48
	v_add_u32_e32 v135, s50, v249
	s_cselect_b32 s49, s21, s46
	s_cselect_b32 s48, s20, s45
	s_add_i32 s51, 0, 0x14000
	ds_read_b128 v[142:145], v135
	ds_read_b128 v[146:149], v135 offset:1024
	ds_read_b128 v[150:153], v135 offset:2048
	ds_read_b128 v[154:157], v135 offset:3072
	v_add_u32_e32 v135, s51, v249
	ds_read_b128 v[158:161], v135
	ds_read_b128 v[162:165], v135 offset:1024
	ds_read_b128 v[166:169], v135 offset:2048
	ds_read_b128 v[170:173], v135 offset:3072
	v_lshl_add_u64 v[174:175], s[22:23], 0, v[138:139]
	s_add_i32 m0, s31, 0xc000
	ds_read_b128 v[182:185], v251
	ds_read_b128 v[186:189], v251 offset:1024
	ds_read_b128 v[190:193], v251 offset:2048
	ds_read_b128 v[194:197], v251 offset:3072
	ds_read_b128 v[198:201], v251 offset:4096
	ds_read_b128 v[202:205], v251 offset:5120
	ds_read_b128 v[206:209], v251 offset:6144
	ds_read_b128 v[210:213], v251 offset:7168
	global_load_lds_dwordx4 v[174:175], off
	v_lshl_add_u64 v[174:175], s[22:23], 0, v[140:141]
	s_add_i32 m0, s31, 0xe000
	s_nop 0
	global_load_lds_dwordx4 v[174:175], off
	s_cmp_gt_u32 s41, 1
	s_cbranch_scc1 .Lpl2_relax_1
	s_waitcnt vmcnt(8)
	s_branch .Lpl2_join_1

.Lpl2_join_1:
	s_waitcnt lgkmcnt(0)
	s_barrier
	s_setprio 1
	s_waitcnt lgkmcnt(0)
	v_mfma_f32_16x16x32_bf16 v[130:133], v[142:145], v[182:185], 0
	v_mfma_f32_16x16x32_bf16 v[130:133], v[146:149], v[186:189], v[130:133]
	v_mfma_f32_16x16x32_bf16 v[126:129], v[150:153], v[182:185], 0
	v_mfma_f32_16x16x32_bf16 v[126:129], v[154:157], v[186:189], v[126:129]
	v_mfma_f32_16x16x32_bf16 v[114:117], v[142:145], v[190:193], 0
	v_mfma_f32_16x16x32_bf16 v[114:117], v[146:149], v[194:197], v[114:117]
	v_mfma_f32_16x16x32_bf16 v[110:113], v[150:153], v[190:193], 0
	v_mfma_f32_16x16x32_bf16 v[110:113], v[154:157], v[194:197], v[110:113]
	v_mfma_f32_16x16x32_bf16 v[98:101], v[142:145], v[198:201], 0
	v_mfma_f32_16x16x32_bf16 v[98:101], v[146:149], v[202:205], v[98:101]
	v_mfma_f32_16x16x32_bf16 v[94:97], v[150:153], v[198:201], 0
	v_mfma_f32_16x16x32_bf16 v[94:97], v[154:157], v[202:205], v[94:97]
	v_mfma_f32_16x16x32_bf16 v[82:85], v[142:145], v[206:209], 0
	v_mfma_f32_16x16x32_bf16 v[82:85], v[146:149], v[210:213], v[82:85]
	v_mfma_f32_16x16x32_bf16 v[78:81], v[150:153], v[206:209], 0
	v_mfma_f32_16x16x32_bf16 v[78:81], v[154:157], v[210:213], v[78:81]
	s_setprio 0
	s_setprio 1
	v_mfma_f32_16x16x32_bf16 v[122:125], v[158:161], v[182:185], 0
	v_mfma_f32_16x16x32_bf16 v[122:125], v[162:165], v[186:189], v[122:125]
	v_mfma_f32_16x16x32_bf16 v[118:121], v[166:169], v[182:185], 0
	v_mfma_f32_16x16x32_bf16 v[118:121], v[170:173], v[186:189], v[118:121]
	v_mfma_f32_16x16x32_bf16 v[106:109], v[158:161], v[190:193], 0
	v_mfma_f32_16x16x32_bf16 v[106:109], v[162:165], v[194:197], v[106:109]
	v_mfma_f32_16x16x32_bf16 v[102:105], v[166:169], v[190:193], 0
	v_mfma_f32_16x16x32_bf16 v[102:105], v[170:173], v[194:197], v[102:105]
	v_mfma_f32_16x16x32_bf16 v[90:93], v[158:161], v[198:201], 0
	v_mfma_f32_16x16x32_bf16 v[90:93], v[162:165], v[202:205], v[90:93]
	v_mfma_f32_16x16x32_bf16 v[86:89], v[166:169], v[198:201], 0
	v_mfma_f32_16x16x32_bf16 v[86:89], v[170:173], v[202:205], v[86:89]
	v_mfma_f32_16x16x32_bf16 v[74:77], v[158:161], v[206:209], 0
	v_mfma_f32_16x16x32_bf16 v[74:77], v[162:165], v[210:213], v[74:77]
	v_mfma_f32_16x16x32_bf16 v[70:73], v[166:169], v[206:209], 0
	v_mfma_f32_16x16x32_bf16 v[70:73], v[170:173], v[210:213], v[70:73]
	s_setprio 0
	s_barrier
	s_add_i32 s50, s50, s30
	v_lshl_add_u64 v[174:175], s[48:49], 0, v[0:1]
	s_mov_b32 m0, s50
	ds_read_b128 v[182:185], v251 offset:16384
	ds_read_b128 v[186:189], v251 offset:17408
	ds_read_b128 v[190:193], v251 offset:18432
	ds_read_b128 v[194:197], v251 offset:19456
	ds_read_b128 v[198:201], v251 offset:20480
	ds_read_b128 v[202:205], v251 offset:21504
	ds_read_b128 v[206:209], v251 offset:22528
	ds_read_b128 v[210:213], v251 offset:23552
	global_load_lds_dwordx4 v[174:175], off
	s_add_i32 m0, s50, 0x2000
	v_lshl_add_u64 v[214:215], s[48:49], 0, v[14:15]
	s_add_u32 s48, s48, s10
	s_addc_u32 s49, s49, 0
	s_add_i32 s50, s51, s30
	global_load_lds_dwordx4 v[214:215], off
	v_lshl_add_u64 v[216:217], s[48:49], 0, v[0:1]
	s_mov_b32 m0, s50
	v_lshl_add_u64 v[218:219], s[48:49], 0, v[14:15]
	global_load_lds_dwordx4 v[216:217], off
	s_add_i32 m0, s50, 0x2000
	v_lshl_add_u64 v[220:221], s[24:25], 0, v[0:1]
	global_load_lds_dwordx4 v[218:219], off
	s_mov_b32 m0, s31
	v_lshl_add_u64 v[222:223], s[24:25], 0, v[14:15]
	global_load_lds_dwordx4 v[220:221], off
	s_mov_b32 m0, s34
	s_nop 0
	global_load_lds_dwordx4 v[222:223], off
	s_cmp_gt_u32 s41, 1
	s_cbranch_scc1 .Lpl2_relax_2
	s_waitcnt vmcnt(8)
	s_branch .Lpl2_join_2

.Lpl2_join_2:
	s_waitcnt lgkmcnt(0)
	s_barrier
	s_setprio 1
	s_waitcnt lgkmcnt(0)
	v_mfma_f32_16x16x32_bf16 v[66:69], v[142:145], v[182:185], 0
	v_mfma_f32_16x16x32_bf16 v[66:69], v[146:149], v[186:189], v[66:69]
	v_mfma_f32_16x16x32_bf16 v[62:65], v[150:153], v[182:185], 0
	v_mfma_f32_16x16x32_bf16 v[62:65], v[154:157], v[186:189], v[62:65]
	v_mfma_f32_16x16x32_bf16 v[50:53], v[142:145], v[190:193], 0
	v_mfma_f32_16x16x32_bf16 v[50:53], v[146:149], v[194:197], v[50:53]
	v_mfma_f32_16x16x32_bf16 v[46:49], v[150:153], v[190:193], 0
	v_mfma_f32_16x16x32_bf16 v[46:49], v[154:157], v[194:197], v[46:49]
	v_mfma_f32_16x16x32_bf16 v[34:37], v[142:145], v[198:201], 0
	v_mfma_f32_16x16x32_bf16 v[34:37], v[146:149], v[202:205], v[34:37]
	v_mfma_f32_16x16x32_bf16 v[30:33], v[150:153], v[198:201], 0
	v_mfma_f32_16x16x32_bf16 v[30:33], v[154:157], v[202:205], v[30:33]
	v_mfma_f32_16x16x32_bf16 v[18:21], v[142:145], v[206:209], 0
	v_mfma_f32_16x16x32_bf16 v[18:21], v[146:149], v[210:213], v[18:21]
	v_mfma_f32_16x16x32_bf16 v[10:13], v[150:153], v[206:209], 0
	v_mfma_f32_16x16x32_bf16 v[10:13], v[154:157], v[210:213], v[10:13]
	s_setprio 0
	s_setprio 1
	v_mfma_f32_16x16x32_bf16 v[58:61], v[158:161], v[182:185], 0
	v_mfma_f32_16x16x32_bf16 v[58:61], v[162:165], v[186:189], v[58:61]
	v_mfma_f32_16x16x32_bf16 v[54:57], v[166:169], v[182:185], 0
	v_mfma_f32_16x16x32_bf16 v[54:57], v[170:173], v[186:189], v[54:57]
	v_mfma_f32_16x16x32_bf16 v[42:45], v[158:161], v[190:193], 0
	v_mfma_f32_16x16x32_bf16 v[42:45], v[162:165], v[194:197], v[42:45]
	v_mfma_f32_16x16x32_bf16 v[38:41], v[166:169], v[190:193], 0
	v_mfma_f32_16x16x32_bf16 v[38:41], v[170:173], v[194:197], v[38:41]
	v_mfma_f32_16x16x32_bf16 v[26:29], v[158:161], v[198:201], 0
	v_mfma_f32_16x16x32_bf16 v[26:29], v[162:165], v[202:205], v[26:29]
	v_mfma_f32_16x16x32_bf16 v[22:25], v[166:169], v[198:201], 0
	v_mfma_f32_16x16x32_bf16 v[22:25], v[170:173], v[202:205], v[22:25]
	v_mfma_f32_16x16x32_bf16 v[6:9], v[158:161], v[206:209], 0
	v_mfma_f32_16x16x32_bf16 v[6:9], v[162:165], v[210:213], v[6:9]
	v_mfma_f32_16x16x32_bf16 v[2:5], v[166:169], v[206:209], 0
	v_mfma_f32_16x16x32_bf16 v[2:5], v[170:173], v[210:213], v[2:5]
	s_setprio 0
	s_barrier
	s_add_i32 s48, 0, 0x18000
	v_add_u32_e32 v135, s48, v249
	s_add_i32 s49, 0, 0x1c000
	ds_read_b128 v[142:145], v135
	ds_read_b128 v[146:149], v135 offset:1024
	ds_read_b128 v[150:153], v135 offset:2048
	ds_read_b128 v[154:157], v135 offset:3072
	v_add_u32_e32 v135, s49, v249
	ds_read_b128 v[158:161], v135
	ds_read_b128 v[162:165], v135 offset:1024
	ds_read_b128 v[166:169], v135 offset:2048
	ds_read_b128 v[170:173], v135 offset:3072
	s_add_u32 s24, s24, s10
	s_addc_u32 s25, s25, 0
	s_mov_b32 m0, s35
	v_lshl_add_u64 v[224:225], s[24:25], 0, v[0:1]
	ds_read_b128 v[182:185], v251 offset:32768
	ds_read_b128 v[186:189], v251 offset:33792
	ds_read_b128 v[190:193], v251 offset:34816
	ds_read_b128 v[194:197], v251 offset:35840
	ds_read_b128 v[198:201], v251 offset:36864
	ds_read_b128 v[202:205], v251 offset:37888
	ds_read_b128 v[206:209], v251 offset:38912
	ds_read_b128 v[210:213], v251 offset:39936
	global_load_lds_dwordx4 v[224:225], off
	v_lshl_add_u64 v[224:225], s[24:25], 0, v[14:15]
	s_mov_b32 m0, s36
	s_nop 0
	global_load_lds_dwordx4 v[224:225], off
	s_waitcnt vmcnt(8)
	s_waitcnt lgkmcnt(0)
	s_barrier
	s_setprio 1
	s_waitcnt lgkmcnt(0)
	v_mfma_f32_16x16x32_bf16 v[130:133], v[142:145], v[182:185], v[130:133]
	v_mfma_f32_16x16x32_bf16 v[130:133], v[146:149], v[186:189], v[130:133]
	v_mfma_f32_16x16x32_bf16 v[126:129], v[150:153], v[182:185], v[126:129]
	v_mfma_f32_16x16x32_bf16 v[126:129], v[154:157], v[186:189], v[126:129]
	v_mfma_f32_16x16x32_bf16 v[114:117], v[142:145], v[190:193], v[114:117]
	v_mfma_f32_16x16x32_bf16 v[114:117], v[146:149], v[194:197], v[114:117]
	v_mfma_f32_16x16x32_bf16 v[110:113], v[150:153], v[190:193], v[110:113]
	v_mfma_f32_16x16x32_bf16 v[110:113], v[154:157], v[194:197], v[110:113]
	v_mfma_f32_16x16x32_bf16 v[98:101], v[142:145], v[198:201], v[98:101]
	v_mfma_f32_16x16x32_bf16 v[98:101], v[146:149], v[202:205], v[98:101]
	v_mfma_f32_16x16x32_bf16 v[94:97], v[150:153], v[198:201], v[94:97]
	v_mfma_f32_16x16x32_bf16 v[94:97], v[154:157], v[202:205], v[94:97]
	v_mfma_f32_16x16x32_bf16 v[82:85], v[142:145], v[206:209], v[82:85]
	v_mfma_f32_16x16x32_bf16 v[82:85], v[146:149], v[210:213], v[82:85]
	v_mfma_f32_16x16x32_bf16 v[78:81], v[150:153], v[206:209], v[78:81]
	v_mfma_f32_16x16x32_bf16 v[78:81], v[154:157], v[210:213], v[78:81]
	s_setprio 0
	s_setprio 1
	v_mfma_f32_16x16x32_bf16 v[122:125], v[158:161], v[182:185], v[122:125]
	v_mfma_f32_16x16x32_bf16 v[122:125], v[162:165], v[186:189], v[122:125]
	v_mfma_f32_16x16x32_bf16 v[118:121], v[166:169], v[182:185], v[118:121]
	v_mfma_f32_16x16x32_bf16 v[118:121], v[170:173], v[186:189], v[118:121]
	v_mfma_f32_16x16x32_bf16 v[106:109], v[158:161], v[190:193], v[106:109]
	v_mfma_f32_16x16x32_bf16 v[106:109], v[162:165], v[194:197], v[106:109]
	v_mfma_f32_16x16x32_bf16 v[102:105], v[166:169], v[190:193], v[102:105]
	v_mfma_f32_16x16x32_bf16 v[102:105], v[170:173], v[194:197], v[102:105]
	v_mfma_f32_16x16x32_bf16 v[90:93], v[158:161], v[198:201], v[90:93]
	v_mfma_f32_16x16x32_bf16 v[90:93], v[162:165], v[202:205], v[90:93]
	v_mfma_f32_16x16x32_bf16 v[86:89], v[166:169], v[198:201], v[86:89]
	v_mfma_f32_16x16x32_bf16 v[86:89], v[170:173], v[202:205], v[86:89]
	v_mfma_f32_16x16x32_bf16 v[74:77], v[158:161], v[206:209], v[74:77]
	v_mfma_f32_16x16x32_bf16 v[74:77], v[162:165], v[210:213], v[74:77]
	v_mfma_f32_16x16x32_bf16 v[70:73], v[166:169], v[206:209], v[70:73]
	v_mfma_f32_16x16x32_bf16 v[70:73], v[170:173], v[210:213], v[70:73]
	s_setprio 0
	s_barrier
	s_add_i32 s24, s48, s30
	v_lshl_add_u64 v[174:175], v[174:175], 0, s[92:93]
	s_mov_b32 m0, s24
	ds_read_b128 v[182:185], v251 offset:49152
	ds_read_b128 v[186:189], v251 offset:50176
	ds_read_b128 v[190:193], v251 offset:51200
	ds_read_b128 v[194:197], v251 offset:52224
	ds_read_b128 v[198:201], v251 offset:53248
	ds_read_b128 v[202:205], v251 offset:54272
	ds_read_b128 v[206:209], v251 offset:55296
	ds_read_b128 v[210:213], v251 offset:56320
	global_load_lds_dwordx4 v[174:175], off
	v_lshl_add_u64 v[174:175], v[214:215], 0, s[92:93]
	s_add_i32 m0, s24, 0x2000
	s_add_i32 s24, s49, s30
	global_load_lds_dwordx4 v[174:175], off
	v_lshl_add_u64 v[174:175], v[216:217], 0, s[92:93]
	s_mov_b32 m0, s24
	s_nop 0
	global_load_lds_dwordx4 v[174:175], off
	v_lshl_add_u64 v[174:175], v[218:219], 0, s[92:93]
	s_add_i32 m0, s24, 0x2000
	s_nop 0
	global_load_lds_dwordx4 v[174:175], off
	v_lshl_add_u64 v[174:175], v[220:221], 0, s[92:93]
	s_mov_b32 m0, s37
	s_nop 0
	global_load_lds_dwordx4 v[174:175], off
	v_lshl_add_u64 v[174:175], v[222:223], 0, s[92:93]
	s_mov_b32 m0, s38
	s_nop 0
	global_load_lds_dwordx4 v[174:175], off
	s_waitcnt vmcnt(8)
	s_waitcnt lgkmcnt(0)
	s_barrier
	s_setprio 1
	s_waitcnt lgkmcnt(0)
	v_mfma_f32_16x16x32_bf16 v[66:69], v[142:145], v[182:185], v[66:69]
	v_mfma_f32_16x16x32_bf16 v[66:69], v[146:149], v[186:189], v[66:69]
	v_mfma_f32_16x16x32_bf16 v[62:65], v[150:153], v[182:185], v[62:65]
	v_mfma_f32_16x16x32_bf16 v[62:65], v[154:157], v[186:189], v[62:65]
	v_mfma_f32_16x16x32_bf16 v[50:53], v[142:145], v[190:193], v[50:53]
	v_mfma_f32_16x16x32_bf16 v[50:53], v[146:149], v[194:197], v[50:53]
	v_mfma_f32_16x16x32_bf16 v[46:49], v[150:153], v[190:193], v[46:49]
	v_mfma_f32_16x16x32_bf16 v[46:49], v[154:157], v[194:197], v[46:49]
	v_mfma_f32_16x16x32_bf16 v[34:37], v[142:145], v[198:201], v[34:37]
	v_mfma_f32_16x16x32_bf16 v[34:37], v[146:149], v[202:205], v[34:37]
	v_mfma_f32_16x16x32_bf16 v[30:33], v[150:153], v[198:201], v[30:33]
	v_mfma_f32_16x16x32_bf16 v[30:33], v[154:157], v[202:205], v[30:33]
	v_mfma_f32_16x16x32_bf16 v[18:21], v[142:145], v[206:209], v[18:21]
	v_mfma_f32_16x16x32_bf16 v[18:21], v[146:149], v[210:213], v[18:21]
	v_mfma_f32_16x16x32_bf16 v[10:13], v[150:153], v[206:209], v[10:13]
	v_mfma_f32_16x16x32_bf16 v[10:13], v[154:157], v[210:213], v[10:13]
	s_setprio 0
	s_setprio 1
	v_mfma_f32_16x16x32_bf16 v[58:61], v[158:161], v[182:185], v[58:61]
	v_mfma_f32_16x16x32_bf16 v[58:61], v[162:165], v[186:189], v[58:61]
	v_mfma_f32_16x16x32_bf16 v[54:57], v[166:169], v[182:185], v[54:57]
	v_mfma_f32_16x16x32_bf16 v[54:57], v[170:173], v[186:189], v[54:57]
	v_mfma_f32_16x16x32_bf16 v[42:45], v[158:161], v[190:193], v[42:45]
	v_mfma_f32_16x16x32_bf16 v[42:45], v[162:165], v[194:197], v[42:45]
	v_mfma_f32_16x16x32_bf16 v[38:41], v[166:169], v[190:193], v[38:41]
	v_mfma_f32_16x16x32_bf16 v[38:41], v[170:173], v[194:197], v[38:41]
	v_mfma_f32_16x16x32_bf16 v[26:29], v[158:161], v[198:201], v[26:29]
	v_mfma_f32_16x16x32_bf16 v[26:29], v[162:165], v[202:205], v[26:29]
	v_mfma_f32_16x16x32_bf16 v[22:25], v[166:169], v[198:201], v[22:25]
	v_mfma_f32_16x16x32_bf16 v[22:25], v[170:173], v[202:205], v[22:25]
	v_mfma_f32_16x16x32_bf16 v[6:9], v[158:161], v[206:209], v[6:9]
	v_mfma_f32_16x16x32_bf16 v[6:9], v[162:165], v[210:213], v[6:9]
	v_mfma_f32_16x16x32_bf16 v[2:5], v[166:169], v[206:209], v[2:5]
	v_mfma_f32_16x16x32_bf16 v[2:5], v[170:173], v[210:213], v[2:5]
	s_setprio 0
	s_barrier
	s_add_u32 s22, s22, 0x100
	s_addc_u32 s23, s23, 0
	s_add_u32 s45, s45, 0x100
	s_addc_u32 s46, s46, 0
	s_cmp_ge_u32 s47, s39
	s_mov_b32 s24, s47
	s_cbranch_scc1 .Lpeel_exit_2

.LBB0_890:
	s_add_i32 s34, s2, 1
	s_mul_i32 s0, s34, s70
	s_mul_hi_u32 s1, s34, s56
	s_add_i32 s1, s1, s0
	s_mul_i32 s0, s34, s56
	s_add_u32 s16, s0, s74
	s_addc_u32 s17, s1, s75
	v_mov_b64_e32 v[2:3], 0xb00
	v_cmp_gt_i64_e32 vcc, s[16:17], v[180:181]
	v_cmp_lt_i64_e64 s[0:1], s[16:17], v[2:3]
	s_cbranch_vccnz .LBB0_892
	s_ashr_i32 s10, s16, 31
	s_lshr_b32 s10, s10, 29
	s_add_i32 s10, s16, s10
	s_ashr_i32 s11, s10, 3
	s_and_b32 s10, s10, -8
	s_sub_i32 s10, s16, s10
	s_cmp_lt_i32 s10, 0
	s_cselect_b32 s14, s79, 0x160
	s_mul_i32 s10, s10, s14
	s_add_i32 s10, s10, s11
	s_mul_hi_i32 s11, s10, 0x2e8ba2e9
	s_lshr_b32 s14, s11, 31
	s_ashr_i32 s11, s11, 5
	s_add_i32 s11, s11, s14
	s_lshl_b32 s14, s11, 3
	s_mulk_i32 s11, 0xb0
	s_sub_i32 s11, s10, s11
	s_lshr_b32 s10, s11, 3
	s_and_b32 s11, s11, 7
	s_add_i32 s14, s14, s11
